# gdnpost token loop: next token's loads issued before the current token's arithmetic (on top of v32)
# baseline (speedup 1.0000x reference)
; __device__ __forceinline__ unsigned cvt_pk(float lo, float hi) { f32x2_t v = {lo, hi}; bf16x2_t b = __builtin_convertvector(v, bf16x2_t); return __builtin_bit_cast(unsigned, b); }
; __device__ __forceinline__ float lo_bf(unsigned u) { return __uint_as_float(u << 16); }
; __device__ __forceinline__ float hi_bf(unsigned u) { return __uint_as_float(u & 0xffff0000u); }
; __device__ __forceinline__ float siluf_(float x) { return x * __builtin_amdgcn_rcpf(1.f + __builtin_amdgcn_exp2f(-1.4426950408889634f * x)); }
; __device__ __forceinline__ int fresh_tid() { int t; asm volatile("v_mov_b32 %0, %1" : "=v"(t) : "v"(threadIdx.x)); return t; }
; __device__ __forceinline__ int fresh_bid() { int t; asm volatile("s_mov_b32 %0, %1" : "=s"(t) : "s"(blockIdx.x)); return t; }
; __device__ __forceinline__ void phase_gdnpost(const Ctx& a, int l, int b) {
;     const bf16_t* pa = (const bf16_t*)(a.ws + B_PROJ); bf16_t* br = (bf16_t*)(a.ws + B_BRANCH);
;     const float* onorm = a.in(I_ONORM) + l * 128;
;     const int tid = fresh_tid(), lane = tid & 63, wv = tid >> 6;
;     float g[8];
; #pragma unroll
;     for (int e = 0; e < 8; ++e) g[e] = onorm[(lane & 15) * 8 + e];
;     for (int tk = fresh_bid() * 8 + wv; tk < SEQ; tk += gridDim.x * 8) {
;         bf16_t* op = br + ((size_t)b * SEQ + tk) * BR + 512 + lane * 8;
;         u32x4 ov = *(const u32x4*)op;
;         u32x4 zv = *(const u32x4*)(pa + (size_t)tk * PA + C_GZ + lane * 8);
;         float x[8]; float ss = 0.f;
; #pragma unroll
;         for (int e = 0; e < 4; ++e) { x[2 * e] = lo_bf(ov[e]); x[2 * e + 1] = hi_bf(ov[e]); ss += x[2 * e] * x[2 * e] + x[2 * e + 1] * x[2 * e + 1]; }
;         ss += __shfl_xor(ss, 1); ss += __shfl_xor(ss, 2); ss += __shfl_xor(ss, 4); ss += __shfl_xor(ss, 8);
;         const float r = rsqrtf(ss * (1.f / 128.f) + EPS);
;         u32x4 w;
; #pragma unroll
;         for (int e = 0; e < 4; ++e) w[e] = cvt_pk(x[2 * e] * r * g[2 * e] * siluf_(lo_bf(zv[e])), x[2 * e + 1] * r * g[2 * e + 1] * siluf_(hi_bf(zv[e])));
;         *(u32x4*)op = w;
;     }
.LBB0_526:
	s_and_b64 vcc, exec, s[92:93]
	s_cbranch_vccz .LBB0_531
	v_readlane_b32 s0, v255, 3
	v_readlane_b32 s1, v255, 4
	s_waitcnt lgkmcnt(0)
	s_nop 3
	global_load_dwordx2 v[2:3], v145, s[0:1]
	v_readlane_b32 s0, v253, 61
	v_readlane_b32 s1, v253, 62
	s_lshl_b64 s[0:1], s[0:1], 2
	v_mov_b32 v1, v179
	s_waitcnt vmcnt(0)
	v_lshlrev_b32_e32 v4, 5, v1
	v_and_b32_e32 v144, 0x1e0, v4
	v_ashrrev_i32_e32 v10, 6, v1
	v_lshl_add_u64 v[2:3], v[2:3], 0, s[0:1]
	v_lshl_add_u64 v[6:7], v[2:3], 0, v[144:145]
	flat_load_dwordx4 v[2:5], v[6:7]
	s_nop 0
	flat_load_dwordx4 v[6:9], v[6:7] offset:16
	s_mov_b32 s0, s2
	s_nop 0
	v_lshl_add_u32 v10, s0, 3, v10
	s_movk_i32 s0, 0x2000
	v_cmp_gt_i32_e32 vcc, s0, v10
	s_and_saveexec_b64 s[0:1], vcc
	v_readlane_b32 s6, v255, 7
	s_movk_i32 s26, 0x1fff
	v_readlane_b32 s7, v255, 8
	s_cbranch_execz .LBB0_530
	v_lshlrev_b32_e32 v1, 3, v1
	v_and_b32_e32 v11, 64, v195
	v_and_b32_e32 v16, 0x1f8, v1
	v_xor_b32_e32 v1, 1, v195
	v_add_u32_e32 v11, 64, v11
	v_cmp_lt_i32_e32 vcc, v1, v11
	v_xor_b32_e32 v12, 2, v195
	s_load_dword s8, s[74:75], 0x0
	v_cndmask_b32_e32 v1, v195, v1, vcc
	v_cmp_lt_i32_e32 vcc, v12, v11
	v_xor_b32_e32 v13, 4, v195
	v_xor_b32_e32 v14, 8, v195
	v_cndmask_b32_e32 v12, v195, v12, vcc
	v_cmp_lt_i32_e32 vcc, v13, v11
	v_lshlrev_b32_e32 v1, 2, v1
	v_lshlrev_b32_e32 v12, 2, v12
	v_cndmask_b32_e32 v13, v195, v13, vcc
	v_cmp_lt_i32_e32 vcc, v14, v11
	v_lshlrev_b32_e32 v13, 2, v13
	s_waitcnt lgkmcnt(0)
	s_lshl_b32 s9, s8, 3
	v_cndmask_b32_e32 v11, v195, v14, vcc
	v_lshlrev_b32_e32 v14, 2, v11
	s_mov_b64 s[12:13], 0
	v_lshlrev_b32_e32 v144, 1, v16
	v_mov_b32_e32 v98, v10
	v_ashrrev_i32_e32 v99, 31, v98
	v_lshl_add_u64 v[100:101], s[6:7], 0, v[98:99]
	v_mov_b64_e32 v[102:103], s[16:17]
	v_mad_u64_u32 v[102:103], s[36:37], v100, s33, v[102:103]
	v_mad_i32_i24 v103, v101, s33, v103
	v_lshl_add_u64 v[100:101], v[102:103], 0, v[144:145]
	v_add_co_u32_e32 v92, vcc, 0x58f4000, v100
	v_lshlrev_b64 v[94:95], 13, v[98:99]
	s_nop 0
	v_addc_co_u32_e32 v93, vcc, 0, v101, vcc
	v_lshl_add_u64 v[94:95], s[16:17], 0, v[94:95]
	global_load_dwordx4 v[84:87], v[92:93], off offset:1536
	v_lshl_add_u64 v[94:95], v[94:95], 0, v[144:145]
	v_add_co_u32_e32 v94, vcc, 0x88f5000, v94
	s_nop 1
	v_addc_co_u32_e32 v95, vcc, 0, v95, vcc
	global_load_dwordx4 v[88:91], v[94:95], off offset:336
.LBB0_529:
	s_waitcnt vmcnt(0)
	v_mov_b32_e32 v16, v84
	v_mov_b32_e32 v17, v85
	v_mov_b32_e32 v18, v86
	v_mov_b32_e32 v19, v87
	v_mov_b32_e32 v20, v88
	v_mov_b32_e32 v21, v89
	v_mov_b32_e32 v22, v90
	v_mov_b32_e32 v23, v91
	v_mov_b32_e32 v24, v92
	v_mov_b32_e32 v25, v93
	v_add_u32_e32 v10, s9, v10
	v_mov_b32_e32 v98, v10
	v_ashrrev_i32_e32 v99, 31, v98
	v_lshl_add_u64 v[100:101], s[6:7], 0, v[98:99]
	v_mov_b64_e32 v[102:103], s[16:17]
	v_mad_u64_u32 v[102:103], s[36:37], v100, s33, v[102:103]
	v_mad_i32_i24 v103, v101, s33, v103
	v_lshl_add_u64 v[100:101], v[102:103], 0, v[144:145]
	v_add_co_u32_e32 v92, vcc, 0x58f4000, v100
	v_lshlrev_b64 v[94:95], 13, v[98:99]
	s_nop 0
	v_addc_co_u32_e32 v93, vcc, 0, v101, vcc
	v_lshl_add_u64 v[94:95], s[16:17], 0, v[94:95]
	global_load_dwordx4 v[84:87], v[92:93], off offset:1536
	v_lshl_add_u64 v[94:95], v[94:95], 0, v[144:145]
	v_add_co_u32_e32 v94, vcc, 0x88f5000, v94
	s_nop 1
	v_addc_co_u32_e32 v95, vcc, 0, v95, vcc
	global_load_dwordx4 v[88:91], v[94:95], off offset:336
	v_and_b32_e32 v27, 0xffff0000, v19
	v_and_b32_e32 v29, 0xffff0000, v18
	v_lshlrev_b32_e32 v26, 16, v19
	v_lshlrev_b32_e32 v28, 16, v18
	v_mov_b32_e32 v30, v27
	v_mov_b32_e32 v31, v29
	v_mov_b32_e32 v18, v26
	v_mov_b32_e32 v19, v28
	v_pk_mul_f32 v[30:31], v[30:31], v[30:31]
	v_lshlrev_b32_e32 v34, 16, v21
	v_pk_fma_f32 v[18:19], v[18:19], v[18:19], v[30:31]
	v_lshlrev_b32_e32 v30, 16, v22
	v_mul_f32_e32 v11, 0xbfb8aa3b, v30
	v_exp_f32_e32 v11, v11
	v_and_b32_e32 v31, 0xffff0000, v22
	v_and_b32_e32 v35, 0xffff0000, v21
	v_add_f32_e32 v11, 1.0, v11
	v_rcp_f32_e32 v32, v11
	v_mul_f32_e32 v11, 0xbfb8aa3b, v31
	v_exp_f32_e32 v11, v11
	s_nop 0
	v_add_f32_e32 v11, 1.0, v11
	v_rcp_f32_e32 v33, v11
	v_mul_f32_e32 v11, 0xbfb8aa3b, v34
	v_exp_f32_e32 v11, v11
	v_pk_mul_f32 v[30:31], v[32:33], v[30:31]
	v_and_b32_e32 v33, 0xffff0000, v17
	v_add_f32_e32 v11, 1.0, v11
	v_rcp_f32_e32 v36, v11
	v_mul_f32_e32 v11, 0xbfb8aa3b, v35
	v_exp_f32_e32 v11, v11
	v_lshlrev_b32_e32 v32, 16, v17
	v_mov_b32_e32 v39, v33
	v_mov_b32_e32 v17, v32
	v_add_f32_e32 v11, 1.0, v11
	v_rcp_f32_e32 v37, v11
	s_nop 0
	v_pk_mul_f32 v[34:35], v[36:37], v[34:35]
	v_and_b32_e32 v37, 0xffff0000, v16
	v_lshlrev_b32_e32 v36, 16, v16
	v_mov_b32_e32 v38, v37
	v_mov_b32_e32 v16, v36
	v_pk_mul_f32 v[38:39], v[38:39], v[38:39]
	s_nop 0
	v_pk_fma_f32 v[16:17], v[16:17], v[16:17], v[38:39]
	v_lshlrev_b32_e32 v38, 16, v20
	v_mul_f32_e32 v11, 0xbfb8aa3b, v38
	v_exp_f32_e32 v11, v11
	v_and_b32_e32 v39, 0xffff0000, v20
	v_add_f32_e32 v11, 1.0, v11
	v_rcp_f32_e32 v20, v11
	v_mul_f32_e32 v11, 0xbfb8aa3b, v39
	v_exp_f32_e32 v11, v11
	s_nop 0
	v_add_f32_e32 v11, 1.0, v11
	v_rcp_f32_e32 v21, v11
	v_add_f32_e32 v11, v16, v17
	v_add_f32_e32 v11, v19, v11
	v_add_f32_e32 v11, v18, v11
	ds_bpermute_b32 v15, v1, v11
	v_pk_mul_f32 v[20:21], v[20:21], v[38:39]
	s_waitcnt lgkmcnt(0)
	v_add_f32_e32 v11, v11, v15
	ds_bpermute_b32 v15, v12, v11
	s_waitcnt lgkmcnt(0)
	v_add_f32_e32 v11, v11, v15
	ds_bpermute_b32 v15, v13, v11
	s_waitcnt lgkmcnt(0)
	v_add_f32_e32 v11, v11, v15
	ds_bpermute_b32 v15, v14, v11
	s_waitcnt lgkmcnt(0)
	v_add_f32_e32 v11, v11, v15
	v_fmamk_f32 v11, v11, 0x3c000000, v178
	v_cmp_gt_f32_e32 vcc, s88, v11
	v_mul_f32_e32 v15, 0x4b800000, v11
	s_nop 0
	v_cndmask_b32_e32 v11, v11, v15, vcc
	v_rsq_f32_e32 v11, v11
	s_nop 0
	v_mul_f32_e32 v15, 0x45800000, v11
	v_cndmask_b32_e32 v22, v11, v15, vcc
	v_pk_mul_f32 v[16:17], v[22:23], v[36:37] op_sel_hi:[0,1]
	v_pk_mul_f32 v[16:17], v[2:3], v[16:17]
	v_pk_mul_f32 v[18:19], v[22:23], v[32:33] op_sel_hi:[0,1]
	v_pk_mul_f32 v[16:17], v[20:21], v[16:17]
	v_lshlrev_b32_e32 v20, 16, v23
	v_mul_f32_e32 v11, 0xbfb8aa3b, v20
	v_exp_f32_e32 v11, v11
	v_pk_mul_f32 v[18:19], v[4:5], v[18:19]
	v_and_b32_e32 v21, 0xffff0000, v23
	v_pk_mul_f32 v[18:19], v[34:35], v[18:19]
	v_add_f32_e32 v11, 1.0, v11
	v_cvt_pk_bf16_f32 v16, v16, v17
	v_cvt_pk_bf16_f32 v17, v18, v19
	v_pk_mul_f32 v[18:19], v[22:23], v[28:29] op_sel_hi:[0,1]
	v_rcp_f32_e32 v28, v11
	v_mul_f32_e32 v11, 0xbfb8aa3b, v21
	v_exp_f32_e32 v11, v11
	v_pk_mul_f32 v[22:23], v[22:23], v[26:27] op_sel_hi:[0,1]
	v_pk_mul_f32 v[18:19], v[6:7], v[18:19]
	v_pk_mul_f32 v[22:23], v[8:9], v[22:23]
	v_add_f32_e32 v11, 1.0, v11
	v_rcp_f32_e32 v29, v11
	v_pk_mul_f32 v[18:19], v[30:31], v[18:19]
	v_cmp_lt_i32_e32 vcc, s26, v10
	v_cvt_pk_bf16_f32 v18, v18, v19
	v_pk_mul_f32 v[20:21], v[28:29], v[20:21]
	s_or_b64 s[12:13], vcc, s[12:13]
	v_pk_mul_f32 v[20:21], v[20:21], v[22:23]
	s_nop 0
	v_cvt_pk_bf16_f32 v19, v20, v21
	global_store_dwordx4 v[24:25], v[16:19], off offset:1536
	s_andn2_b64 exec, exec, s[12:13]
	s_cbranch_execnz .LBB0_529
